# attention S=KQ^T: K-fragment LDS reads issued five deep into a register ring (was one ahead); MFMA order unchanged
# baseline (speedup 1.0000x reference)
.LBB0_473:
	v_lshl_add_u64 v[34:35], v[134:135], 0, s[16:17]
	v_lshl_add_u64 v[36:37], s[10:11], 0, v[132:133]
	v_cndmask_b32_e32 v35, v35, v37, vcc
	v_cndmask_b32_e32 v34, v34, v36, vcc
	s_barrier
	s_waitcnt vmcnt(4)
	ds_write_b128 v140, v[90:93]
	s_waitcnt vmcnt(3)
	ds_write_b128 v141, v[94:97]
	s_waitcnt vmcnt(0)
	ds_write_b128 v142, v[98:101]
	ds_write_b128 v143, v[106:109] offset:13312
	ds_write_b128 v144, v[102:105] offset:13312
	s_waitcnt lgkmcnt(0)
	s_barrier
	global_load_dwordx4 v[90:93], v[34:35], off
	v_lshl_add_u64 v[34:35], s[10:11], 0, v[130:131]
	v_lshl_add_u64 v[36:37], v[128:129], 0, s[16:17]
	v_cndmask_b32_e64 v35, v37, v35, s[42:43]
	v_cndmask_b32_e64 v34, v36, v34, s[42:43]
	global_load_dwordx4 v[94:97], v[34:35], off
	v_lshl_add_u64 v[34:35], s[10:11], 0, v[126:127]
	v_lshl_add_u64 v[36:37], v[124:125], 0, s[16:17]
	v_cndmask_b32_e64 v35, v37, v35, s[44:45]
	v_cndmask_b32_e64 v34, v36, v34, s[44:45]
	global_load_dwordx4 v[98:101], v[34:35], off
	global_load_dwordx4 v[106:109], v[122:123], off
	global_load_dwordx4 v[102:105], v[120:121], off
	v_mov_b32_e32 v147, v146
	v_mov_b32_e32 v0, v148
	ds_read_b128 v[34:37], v139
	ds_read_b128 v[38:41], v136 offset:6656
	ds_read_b128 v[110:113], v136 offset:32
	ds_read_b128 v[114:117], v136 offset:6688
	ds_read_b128 v[236:239], v136 offset:64
	ds_read_b128 v[240:243], v136 offset:6720
	ds_read_b128 v[250:253], v136 offset:96
	s_waitcnt lgkmcnt(6)
	v_mfma_f32_32x32x16_bf16 v[50:65], v[34:37], v[86:89], 0
	s_waitcnt lgkmcnt(5)
	v_mfma_f32_32x32x16_bf16 v[34:49], v[38:41], v[86:89], 0
	s_waitcnt lgkmcnt(4)
	v_mfma_f32_32x32x16_bf16 v[50:65], v[110:113], v[82:85], v[50:65]
	ds_read_b128 v[110:113], v136 offset:6752
	s_waitcnt lgkmcnt(4)
	v_mfma_f32_32x32x16_bf16 v[34:49], v[114:117], v[82:85], v[34:49]
	ds_read_b128 v[114:117], v136 offset:128
	s_waitcnt lgkmcnt(4)
	v_mfma_f32_32x32x16_bf16 v[50:65], v[236:239], v[78:81], v[50:65]
	ds_read_b128 v[236:239], v136 offset:6784
	s_waitcnt lgkmcnt(4)
	v_mfma_f32_32x32x16_bf16 v[34:49], v[240:243], v[78:81], v[34:49]
	ds_read_b128 v[240:243], v136 offset:160
	s_waitcnt lgkmcnt(4)
	v_mfma_f32_32x32x16_bf16 v[50:65], v[250:253], v[74:77], v[50:65]
	ds_read_b128 v[250:253], v136 offset:6816
	s_waitcnt lgkmcnt(4)
	v_mfma_f32_32x32x16_bf16 v[34:49], v[110:113], v[74:77], v[34:49]
	s_waitcnt lgkmcnt(3)
	v_mfma_f32_32x32x16_bf16 v[50:65], v[114:117], v[70:73], v[50:65]
	s_waitcnt lgkmcnt(2)
	v_mfma_f32_32x32x16_bf16 v[34:49], v[236:239], v[70:73], v[34:49]
	s_waitcnt lgkmcnt(1)
	v_mfma_f32_32x32x16_bf16 v[50:65], v[240:243], v[66:69], v[50:65]
	s_waitcnt lgkmcnt(0)
	v_mfma_f32_32x32x16_bf16 v[34:49], v[250:253], v[66:69], v[34:49]
	s_nop 11
	v_max_f32_e32 v110, v34, v34
	v_max_f32_e32 v111, v50, v50
	v_max_f32_e32 v110, v111, v110
	v_max3_f32 v110, v110, v51, v35
	v_max3_f32 v110, v110, v52, v36
	v_max3_f32 v110, v110, v53, v37
	v_max3_f32 v110, v110, v54, v38
	v_max3_f32 v110, v110, v55, v39
	v_max3_f32 v110, v110, v56, v40
	v_max3_f32 v110, v110, v57, v41
	v_max3_f32 v110, v110, v58, v42
	v_max3_f32 v110, v110, v59, v43
	v_max3_f32 v110, v110, v60, v44
	v_max3_f32 v110, v110, v61, v45
	v_max3_f32 v110, v110, v62, v46
	v_max3_f32 v110, v110, v63, v47
	v_max3_f32 v110, v110, v64, v48
	v_max3_f32 v146, v110, v65, v49
	ds_bpermute_b32 v148, v155, v146
	v_add_u32_e32 v137, 0x3000, v145
	v_add_u32_e32 v119, 0x4000, v145
	ds_read2_b64 v[114:117], v137 offset0:128 offset1:130
	ds_read2_b64 v[110:113], v119 offset0:192 offset1:194
	s_waitcnt lgkmcnt(2)
	v_max_f32_e32 v148, v148, v148
	v_max_f32_e32 v146, v146, v148
	v_mul_f32_e32 v146, 0x3e16c740, v146
	v_max_f32_e32 v148, v0, v0
	v_max_f32_e32 v148, v148, v146
	v_sub_f32_e32 v0, v0, v148
	v_fma_f32 v50, v50, s7, -v148
	v_exp_f32_e32 v0, v0
	v_exp_f32_e32 v50, v50
	v_fma_f32 v51, v51, s7, -v148
	v_exp_f32_e32 v51, v51
	s_nop 0
	s_nop 0
	v_fma_f32 v52, v52, s7, -v148
	v_add_f32_e32 v146, 0, v50
	v_fma_f32 v34, v34, s7, -v148
	s_nop 0
	v_exp_f32_e32 v52, v52
	v_fma_f32 v53, v53, s7, -v148
	v_add_f32_e32 v146, v146, v51
	v_exp_f32_e32 v149, v34
	v_fma_f32 v34, v35, s7, -v148
	v_exp_f32_e32 v53, v53
	s_nop 0
	v_fma_f32 v54, v54, s7, -v148
	v_add_f32_e32 v146, v146, v52
	v_exp_f32_e32 v150, v34
	v_fma_f32 v34, v36, s7, -v148
	s_nop 0
	v_exp_f32_e32 v54, v54
	v_fma_f32 v55, v55, s7, -v148
	v_add_f32_e32 v146, v146, v53
	v_exp_f32_e32 v151, v34
	v_fma_f32 v34, v37, s7, -v148
	v_exp_f32_e32 v55, v55
	s_nop 0
	v_fma_f32 v56, v56, s7, -v148
	v_add_f32_e32 v146, v146, v54
	v_exp_f32_e32 v152, v34
	v_fma_f32 v34, v38, s7, -v148
	s_nop 0
	v_exp_f32_e32 v56, v56
	v_fma_f32 v57, v57, s7, -v148
	v_add_f32_e32 v146, v146, v55
	v_exp_f32_e32 v153, v34
	v_fma_f32 v34, v39, s7, -v148
	v_exp_f32_e32 v57, v57
	s_nop 0
	v_fma_f32 v58, v58, s7, -v148
	v_add_f32_e32 v146, v146, v56
	v_exp_f32_e32 v160, v34
	v_fma_f32 v34, v40, s7, -v148
	s_nop 0
	v_exp_f32_e32 v58, v58
	v_fma_f32 v59, v59, s7, -v148
	v_add_f32_e32 v146, v146, v57
	v_exp_f32_e32 v161, v34
	v_fma_f32 v34, v41, s7, -v148
	v_exp_f32_e32 v59, v59
	s_nop 0
	v_fma_f32 v60, v60, s7, -v148
	v_add_f32_e32 v146, v146, v58
	v_exp_f32_e32 v162, v34
	v_fma_f32 v34, v42, s7, -v148
	s_nop 0
	v_exp_f32_e32 v60, v60
	v_fma_f32 v61, v61, s7, -v148
	v_add_f32_e32 v146, v146, v59
	v_exp_f32_e32 v163, v34
	v_fma_f32 v34, v43, s7, -v148
	v_exp_f32_e32 v61, v61
	s_nop 0
	v_fma_f32 v62, v62, s7, -v148
	v_add_f32_e32 v146, v146, v60
	v_exp_f32_e32 v164, v34
	v_fma_f32 v34, v44, s7, -v148
	s_nop 0
	v_exp_f32_e32 v62, v62
	v_fma_f32 v63, v63, s7, -v148
	v_add_f32_e32 v146, v146, v61
	v_exp_f32_e32 v165, v34
	v_fma_f32 v34, v45, s7, -v148
	v_exp_f32_e32 v63, v63
	s_nop 0
	v_fma_f32 v64, v64, s7, -v148
	v_add_f32_e32 v146, v146, v62
	v_exp_f32_e32 v166, v34
	v_fma_f32 v34, v46, s7, -v148
	s_nop 0
	v_exp_f32_e32 v64, v64
	v_fma_f32 v65, v65, s7, -v148
	v_add_f32_e32 v146, v146, v63
	v_exp_f32_e32 v167, v34
	v_fma_f32 v34, v47, s7, -v148
	v_exp_f32_e32 v65, v65
	s_nop 0
	v_exp_f32_e32 v168, v34
	v_add_f32_e32 v146, v146, v64
	v_fma_f32 v34, v48, s7, -v148
	s_nop 0
	v_exp_f32_e32 v169, v34
	v_add_f32_e32 v146, v146, v65
	v_fma_f32 v34, v49, s7, -v148
	s_nop 0
	v_exp_f32_e32 v172, v34
	v_add_f32_e32 v34, v146, v149
	s_nop 0
	s_nop 0
	s_nop 0
	s_nop 0
	s_nop 0
	s_nop 0
	s_nop 0
	v_add_f32_e32 v34, v34, v150
	v_add_f32_e32 v34, v34, v151
	v_add_f32_e32 v34, v34, v152
	v_add_f32_e32 v34, v34, v153
	v_add_f32_e32 v34, v34, v160
	v_add_f32_e32 v34, v34, v161
	s_nop 0
	s_nop 0
	s_nop 0
	s_nop 0
	s_nop 0
	s_nop 0
	s_nop 0
	v_add_f32_e32 v34, v34, v162
	v_add_f32_e32 v34, v34, v163
	v_add_f32_e32 v34, v34, v164
	v_add_f32_e32 v34, v34, v165
	v_add_f32_e32 v34, v34, v166
	v_add_f32_e32 v34, v34, v167
	s_nop 0
	s_nop 0
	s_nop 0
	v_pk_mul_f32 v[32:33], v[32:33], v[0:1] op_sel_hi:[1,0]
	v_add_f32_e32 v34, v34, v168
	v_add_f32_e32 v34, v34, v169
	v_add_f32_e32 v146, v34, v172
	ds_read2_b64 v[34:37], v137 offset0:132 offset1:134
	ds_read2_b64 v[38:41], v119 offset0:196 offset1:198
	v_pk_mul_f32 v[30:31], v[30:31], v[0:1] op_sel_hi:[1,0]
	v_pk_mul_f32 v[28:29], v[28:29], v[0:1] op_sel_hi:[1,0]
	v_pk_mul_f32 v[26:27], v[26:27], v[0:1] op_sel_hi:[1,0]
	v_pk_mul_f32 v[24:25], v[24:25], v[0:1] op_sel_hi:[1,0]
	v_pk_mul_f32 v[22:23], v[22:23], v[0:1] op_sel_hi:[1,0]
	v_pk_mul_f32 v[20:21], v[20:21], v[0:1] op_sel_hi:[1,0]
	v_pk_mul_f32 v[18:19], v[18:19], v[0:1] op_sel_hi:[1,0]
	v_pk_mul_f32 v[16:17], v[16:17], v[0:1] op_sel_hi:[1,0]
	v_pk_mul_f32 v[14:15], v[14:15], v[0:1] op_sel_hi:[1,0]
	v_pk_mul_f32 v[12:13], v[12:13], v[0:1] op_sel_hi:[1,0]
	v_pk_mul_f32 v[10:11], v[10:11], v[0:1] op_sel_hi:[1,0]
	v_pk_mul_f32 v[8:9], v[8:9], v[0:1] op_sel_hi:[1,0]
	v_pk_mul_f32 v[6:7], v[6:7], v[0:1] op_sel_hi:[1,0]
	v_pk_mul_f32 v[4:5], v[4:5], v[0:1] op_sel_hi:[1,0]
	v_pk_mul_f32 v[2:3], v[2:3], v[0:1] op_sel_hi:[1,0]
	v_cvt_pk_bf16_f32 v42, v50, v51
	v_cvt_pk_bf16_f32 v43, v52, v53
	v_cvt_pk_bf16_f32 v44, v54, v55
	v_cvt_pk_bf16_f32 v45, v56, v57
	s_waitcnt lgkmcnt(3)
	s_nop 0
	v_mfma_f32_32x32x16_bf16 v[18:33], v[114:117], v[42:45], v[18:33]
	s_waitcnt lgkmcnt(2)
	v_mfma_f32_32x32x16_bf16 v[2:17], v[110:113], v[42:45], v[2:17]
	ds_read2_b64 v[42:45], v137 offset0:136 offset1:138
	ds_read2_b64 v[46:49], v119 offset0:200 offset1:202
	v_cvt_pk_bf16_f32 v50, v58, v59
	v_cvt_pk_bf16_f32 v51, v60, v61
	v_cvt_pk_bf16_f32 v52, v62, v63
	v_cvt_pk_bf16_f32 v53, v64, v65
	s_waitcnt lgkmcnt(3)
	s_nop 0
	v_mfma_f32_32x32x16_bf16 v[18:33], v[34:37], v[50:53], v[18:33]
	s_waitcnt lgkmcnt(2)
	v_mfma_f32_32x32x16_bf16 v[2:17], v[38:41], v[50:53], v[2:17]
	ds_read2_b64 v[34:37], v137 offset0:140 offset1:142
	ds_read2_b64 v[38:41], v119 offset0:204 offset1:206
	v_cvt_pk_bf16_f32 v50, v149, v150
	v_cvt_pk_bf16_f32 v51, v151, v152
	v_cvt_pk_bf16_f32 v52, v153, v160
	v_cvt_pk_bf16_f32 v53, v161, v162
	s_waitcnt lgkmcnt(3)
	s_nop 0
	v_mfma_f32_32x32x16_bf16 v[18:33], v[42:45], v[50:53], v[18:33]
	s_waitcnt lgkmcnt(2)
	v_mfma_f32_32x32x16_bf16 v[2:17], v[46:49], v[50:53], v[2:17]
	v_cvt_pk_bf16_f32 v42, v163, v164
	v_cvt_pk_bf16_f32 v43, v165, v166
	v_cvt_pk_bf16_f32 v44, v167, v168
	v_cvt_pk_bf16_f32 v45, v169, v172
	s_waitcnt lgkmcnt(1)
	s_nop 0
	v_mfma_f32_32x32x16_bf16 v[18:33], v[34:37], v[42:45], v[18:33]
	s_waitcnt lgkmcnt(0)
	v_mfma_f32_32x32x16_bf16 v[2:17], v[38:41], v[42:45], v[2:17]
	s_add_u32 s16, s16, 0x2000
	s_addc_u32 s17, s17, 0
	s_add_u32 s10, s10, 0x1000
	s_addc_u32 s11, s11, 0
	v_fmac_f32_e32 v146, v147, v0
	v_lshl_add_u64 v[120:121], v[120:121], 0, s[36:37]
	s_cmp_lg_u32 s20, s16
	v_lshl_add_u64 v[122:123], v[122:123], 0, s[36:37]
	s_cbranch_scc1 .LBB0_473
	v_or_b32_e32 v0, 32, v138
	s_barrier
	s_waitcnt vmcnt(4)
	ds_write_b128 v140, v[90:93]
	s_waitcnt vmcnt(3)
	ds_write_b128 v141, v[94:97]
	s_waitcnt vmcnt(2)
	ds_write_b128 v142, v[98:101]
	s_waitcnt vmcnt(1)
	ds_write_b128 v143, v[106:109] offset:13312
	s_waitcnt vmcnt(0)
	ds_write_b128 v144, v[102:105] offset:13312
	s_waitcnt lgkmcnt(0)
	s_barrier
	v_mul_u32_u24_e32 v0, 0xd0, v0
	v_add3_u32 v0, 16, v0, v118
	ds_read_b128 v[34:37], v139
	ds_read_b128 v[38:41], v0
	s_waitcnt lgkmcnt(1)
	v_mfma_f32_32x32x16_bf16 v[50:65], v[34:37], v[86:89], 0
	ds_read_b128 v[90:93], v136 offset:32
	s_waitcnt lgkmcnt(1)
	v_mfma_f32_32x32x16_bf16 v[34:49], v[38:41], v[86:89], 0
	ds_read_b128 v[86:89], v0 offset:32
	s_waitcnt lgkmcnt(1)
	v_mfma_f32_32x32x16_bf16 v[50:65], v[90:93], v[82:85], v[50:65]
	ds_read_b128 v[90:93], v136 offset:64
	s_waitcnt lgkmcnt(1)
	v_mfma_f32_32x32x16_bf16 v[34:49], v[86:89], v[82:85], v[34:49]
	ds_read_b128 v[82:85], v0 offset:64
	s_waitcnt lgkmcnt(1)
	v_mfma_f32_32x32x16_bf16 v[50:65], v[90:93], v[78:81], v[50:65]
	ds_read_b128 v[86:89], v136 offset:96
	s_waitcnt lgkmcnt(1)
	v_mfma_f32_32x32x16_bf16 v[34:49], v[82:85], v[78:81], v[34:49]
	ds_read_b128 v[78:81], v0 offset:96
	s_waitcnt lgkmcnt(1)
	v_mfma_f32_32x32x16_bf16 v[50:65], v[86:89], v[74:77], v[50:65]
	ds_read_b128 v[82:85], v136 offset:128
	s_waitcnt lgkmcnt(1)
	v_mfma_f32_32x32x16_bf16 v[34:49], v[78:81], v[74:77], v[34:49]
	ds_read_b128 v[74:77], v0 offset:128
	s_waitcnt lgkmcnt(1)
	v_mfma_f32_32x32x16_bf16 v[50:65], v[82:85], v[70:73], v[50:65]
	ds_read_b128 v[78:81], v136 offset:160
	s_waitcnt lgkmcnt(1)
	v_mfma_f32_32x32x16_bf16 v[34:49], v[74:77], v[70:73], v[34:49]
	ds_read_b128 v[70:73], v0 offset:160
	s_waitcnt lgkmcnt(1)
	v_mfma_f32_32x32x16_bf16 v[50:65], v[78:81], v[66:69], v[50:65]
	s_waitcnt lgkmcnt(0)
	v_mfma_f32_32x32x16_bf16 v[34:49], v[70:73], v[66:69], v[34:49]
	s_nop 11
	v_max_f32_e32 v0, v34, v34
	v_max_f32_e32 v66, v50, v50
	v_max_f32_e32 v0, v66, v0
	v_max3_f32 v0, v0, v51, v35
	v_max3_f32 v0, v0, v52, v36
	v_max3_f32 v0, v0, v53, v37
	v_max3_f32 v0, v0, v54, v38
	v_max3_f32 v0, v0, v55, v39
	v_max3_f32 v0, v0, v56, v40
	v_max3_f32 v0, v0, v57, v41
	v_max3_f32 v0, v0, v58, v42
	v_max3_f32 v0, v0, v59, v43
	v_max3_f32 v0, v0, v60, v44
	v_max3_f32 v0, v0, v61, v45
	v_max3_f32 v0, v0, v62, v46
	v_max3_f32 v0, v0, v63, v47
	v_max3_f32 v0, v0, v64, v48
	v_max3_f32 v0, v0, v65, v49
	ds_bpermute_b32 v74, v155, v0
	v_max_f32_e32 v75, v148, v148
	ds_read2_b64 v[70:73], v137 offset0:128 offset1:130
	ds_read2_b64 v[66:69], v119 offset0:192 offset1:194
	s_waitcnt lgkmcnt(2)
	v_max_f32_e32 v74, v74, v74
	v_max_f32_e32 v0, v0, v74
	v_mul_f32_e32 v0, 0x3e16c740, v0
	v_max_f32_e32 v74, v75, v0
	v_fma_f32 v34, v34, s7, -v74
	v_fma_f32 v50, v50, s7, -v74
	v_exp_f32_e32 v79, v34
	v_fma_f32 v34, v35, s7, -v74
	v_exp_f32_e32 v75, v50
	v_fma_f32 v50, v52, s7, -v74
	v_exp_f32_e32 v80, v34
	v_fma_f32 v34, v36, s7, -v74
	v_exp_f32_e32 v77, v50
	v_fma_f32 v50, v53, s7, -v74
	v_exp_f32_e32 v81, v34
	v_fma_f32 v34, v37, s7, -v74
	v_exp_f32_e32 v78, v50
	v_fma_f32 v50, v54, s7, -v74
	v_exp_f32_e32 v82, v34
	v_fma_f32 v34, v38, s7, -v74
	v_exp_f32_e32 v54, v50
	v_fma_f32 v50, v55, s7, -v74
	v_exp_f32_e32 v83, v34
	v_fma_f32 v34, v39, s7, -v74
	v_exp_f32_e32 v55, v50
	v_fma_f32 v50, v56, s7, -v74
	v_exp_f32_e32 v84, v34
	v_fma_f32 v34, v40, s7, -v74
	v_exp_f32_e32 v56, v50
	v_fma_f32 v50, v57, s7, -v74
	v_exp_f32_e32 v85, v34
	v_fma_f32 v34, v41, s7, -v74
	v_exp_f32_e32 v57, v50
	v_fma_f32 v50, v58, s7, -v74
	v_exp_f32_e32 v86, v34
	v_fma_f32 v34, v42, s7, -v74
	v_exp_f32_e32 v58, v50
	v_fma_f32 v50, v59, s7, -v74
	v_exp_f32_e32 v87, v34
	v_fma_f32 v34, v43, s7, -v74
	v_exp_f32_e32 v59, v50
	v_fma_f32 v50, v60, s7, -v74
	v_exp_f32_e32 v88, v34
	v_fma_f32 v34, v44, s7, -v74
	v_exp_f32_e32 v60, v50
	v_fma_f32 v50, v61, s7, -v74
	v_exp_f32_e32 v89, v34
	v_fma_f32 v34, v45, s7, -v74
	v_exp_f32_e32 v61, v50
	v_fma_f32 v50, v62, s7, -v74
	v_exp_f32_e32 v90, v34
	v_fma_f32 v34, v46, s7, -v74
	v_exp_f32_e32 v62, v50
	v_fma_f32 v50, v63, s7, -v74
	v_exp_f32_e32 v91, v34
	v_fma_f32 v34, v47, s7, -v74
	v_exp_f32_e32 v63, v50
	v_fma_f32 v50, v64, s7, -v74
	v_exp_f32_e32 v92, v34
	v_fma_f32 v34, v48, s7, -v74
	v_sub_f32_e32 v0, v148, v74
	v_fma_f32 v51, v51, s7, -v74
	v_exp_f32_e32 v64, v50
	v_fma_f32 v50, v65, s7, -v74
	v_exp_f32_e32 v93, v34
	v_fma_f32 v34, v49, s7, -v74
	v_exp_f32_e32 v0, v0
	v_exp_f32_e32 v76, v51
	v_exp_f32_e32 v65, v50
	v_exp_f32_e32 v74, v34
	s_nop 0
	s_nop 0
	s_nop 0
	s_nop 0
	s_nop 0
	s_nop 0
	s_nop 0
	s_nop 0
	s_nop 0
	s_nop 0
	s_nop 0
	s_nop 0
	s_nop 0
	s_nop 0
	s_nop 0
	s_nop 0
	s_nop 0
	s_nop 0
	s_nop 0
	s_nop 0
	s_nop 0
	s_nop 0
	s_nop 0
	s_nop 0
	s_nop 0
	s_nop 0
	s_nop 0
	s_nop 0
	s_nop 0
	s_nop 0
	s_nop 0
	s_nop 0
	s_nop 0
	ds_read2_b64 v[34:37], v137 offset0:132 offset1:134
	ds_read2_b64 v[38:41], v119 offset0:196 offset1:198
	v_pk_mul_f32 v[32:33], v[32:33], v[0:1] op_sel_hi:[1,0]
	v_pk_mul_f32 v[30:31], v[30:31], v[0:1] op_sel_hi:[1,0]
	v_pk_mul_f32 v[28:29], v[28:29], v[0:1] op_sel_hi:[1,0]
	v_pk_mul_f32 v[26:27], v[26:27], v[0:1] op_sel_hi:[1,0]
	v_pk_mul_f32 v[24:25], v[24:25], v[0:1] op_sel_hi:[1,0]
	v_pk_mul_f32 v[22:23], v[22:23], v[0:1] op_sel_hi:[1,0]
	v_pk_mul_f32 v[20:21], v[20:21], v[0:1] op_sel_hi:[1,0]
	v_pk_mul_f32 v[18:19], v[18:19], v[0:1] op_sel_hi:[1,0]
	v_pk_mul_f32 v[16:17], v[16:17], v[0:1] op_sel_hi:[1,0]
	v_pk_mul_f32 v[14:15], v[14:15], v[0:1] op_sel_hi:[1,0]
	v_pk_mul_f32 v[12:13], v[12:13], v[0:1] op_sel_hi:[1,0]
	v_pk_mul_f32 v[10:11], v[10:11], v[0:1] op_sel_hi:[1,0]
	v_pk_mul_f32 v[8:9], v[8:9], v[0:1] op_sel_hi:[1,0]
	v_pk_mul_f32 v[6:7], v[6:7], v[0:1] op_sel_hi:[1,0]
	v_pk_mul_f32 v[4:5], v[4:5], v[0:1] op_sel_hi:[1,0]
	v_pk_mul_f32 v[2:3], v[2:3], v[0:1] op_sel_hi:[1,0]
	v_cvt_pk_bf16_f32 v42, v75, v76
	v_cvt_pk_bf16_f32 v43, v77, v78
	v_cvt_pk_bf16_f32 v44, v54, v55
	v_cvt_pk_bf16_f32 v45, v56, v57
	s_waitcnt lgkmcnt(3)
	s_nop 0
	v_mfma_f32_32x32x16_bf16 v[18:33], v[70:73], v[42:45], v[18:33]
	s_waitcnt lgkmcnt(2)
	v_mfma_f32_32x32x16_bf16 v[2:17], v[66:69], v[42:45], v[2:17]
	ds_read2_b64 v[42:45], v137 offset0:136 offset1:138
	ds_read2_b64 v[46:49], v119 offset0:200 offset1:202
	v_cvt_pk_bf16_f32 v50, v58, v59
	v_cvt_pk_bf16_f32 v51, v60, v61
	v_cvt_pk_bf16_f32 v52, v62, v63
	v_cvt_pk_bf16_f32 v53, v64, v65
	s_waitcnt lgkmcnt(3)
	s_nop 0
	v_mfma_f32_32x32x16_bf16 v[18:33], v[34:37], v[50:53], v[18:33]
	s_waitcnt lgkmcnt(2)
	v_mfma_f32_32x32x16_bf16 v[2:17], v[38:41], v[50:53], v[2:17]
	ds_read2_b64 v[34:37], v137 offset0:140 offset1:142
	ds_read2_b64 v[38:41], v119 offset0:204 offset1:206
	v_cvt_pk_bf16_f32 v50, v79, v80
	v_cvt_pk_bf16_f32 v51, v81, v82
	v_cvt_pk_bf16_f32 v52, v83, v84
	v_cvt_pk_bf16_f32 v53, v85, v86
	s_waitcnt lgkmcnt(3)
	s_nop 0
	v_mfma_f32_32x32x16_bf16 v[18:33], v[42:45], v[50:53], v[18:33]
	s_waitcnt lgkmcnt(2)
	v_mfma_f32_32x32x16_bf16 v[2:17], v[46:49], v[50:53], v[2:17]
	v_cvt_pk_bf16_f32 v42, v87, v88
	v_cvt_pk_bf16_f32 v43, v89, v90
	v_cvt_pk_bf16_f32 v44, v91, v92
	v_cvt_pk_bf16_f32 v45, v93, v74
	s_waitcnt lgkmcnt(1)
	s_nop 0
	v_mfma_f32_32x32x16_bf16 v[18:33], v[34:37], v[42:45], v[18:33]
	s_waitcnt lgkmcnt(0)
	v_mfma_f32_32x32x16_bf16 v[2:17], v[38:41], v[42:45], v[2:17]
	v_add_f32_e32 v34, 0, v75
	v_add_f32_e32 v34, v34, v76
	v_add_f32_e32 v34, v34, v77
	v_add_f32_e32 v34, v34, v78
	v_add_f32_e32 v34, v34, v54
	v_add_f32_e32 v34, v34, v55
	v_add_f32_e32 v34, v34, v56
	v_add_f32_e32 v34, v34, v57
	v_add_f32_e32 v34, v34, v58
	v_add_f32_e32 v34, v34, v59
	v_add_f32_e32 v34, v34, v60
	v_add_f32_e32 v34, v34, v61
	v_add_f32_e32 v34, v34, v62
	v_add_f32_e32 v34, v34, v63
	v_add_f32_e32 v34, v34, v64
	v_add_f32_e32 v34, v34, v65
	v_add_f32_e32 v34, v34, v79
	v_add_f32_e32 v34, v34, v80
	v_add_f32_e32 v34, v34, v81
	v_add_f32_e32 v34, v34, v82
	v_add_f32_e32 v34, v34, v83
	v_add_f32_e32 v34, v34, v84
	v_add_f32_e32 v34, v34, v85
	v_add_f32_e32 v34, v34, v86
	v_add_f32_e32 v34, v34, v87
	v_add_f32_e32 v34, v34, v88
	v_add_f32_e32 v34, v34, v89
	v_add_f32_e32 v34, v34, v90
	v_add_f32_e32 v34, v34, v91
	v_add_f32_e32 v34, v34, v92
	v_add_f32_e32 v34, v34, v93
	v_add_f32_e32 v34, v34, v74
	v_fmac_f32_e32 v34, v146, v0
	ds_bpermute_b32 v0, v155, v34
	s_waitcnt lgkmcnt(0)
	v_add_f32_e32 v0, v34, v0
	v_div_scale_f32 v34, s[10:11], v0, v0, 1.0
	v_rcp_f32_e32 v35, v34
	v_div_scale_f32 v36, vcc, 1.0, v0, 1.0
	s_lshl_b32 s10, s2, 7
	v_fma_f32 v37, -v34, v35, 1.0
	v_fmac_f32_e32 v35, v37, v35
	v_mul_f32_e32 v37, v36, v35
	v_fma_f32 v38, -v34, v37, v36
	v_fmac_f32_e32 v37, v38, v35
	v_fma_f32 v34, -v34, v37, v36
	v_div_fmas_f32 v34, v34, v35, v37
	v_div_fixup_f32 v0, v34, v0, 1.0
	v_add_u32_e32 v34, s6, v171
	v_ashrrev_i32_e32 v35, 31, v34
	v_lshlrev_b64 v[34:35], 11, v[34:35]
	v_lshl_add_u64 v[34:35], s[56:57], 0, v[34:35]
	s_mov_b32 s11, s3
	v_pk_mul_f32 v[18:19], v[18:19], v[0:1] op_sel_hi:[1,0]
	v_pk_mul_f32 v[20:21], v[20:21], v[0:1] op_sel_hi:[1,0]
	v_pk_mul_f32 v[2:3], v[2:3], v[0:1] op_sel_hi:[1,0]
	v_pk_mul_f32 v[4:5], v[4:5], v[0:1] op_sel_hi:[1,0]
	v_lshl_add_u64 v[34:35], v[34:35], 0, s[10:11]
	v_lshlrev_b32_e32 v36, 1, v154
	v_mov_b32_e32 v37, v1
	v_pk_mul_f32 v[22:23], v[22:23], v[0:1] op_sel_hi:[1,0]
	v_pk_mul_f32 v[24:25], v[24:25], v[0:1] op_sel_hi:[1,0]
	v_pk_mul_f32 v[6:7], v[6:7], v[0:1] op_sel_hi:[1,0]
	v_pk_mul_f32 v[8:9], v[8:9], v[0:1] op_sel_hi:[1,0]
	v_lshl_add_u64 v[34:35], v[34:35], 0, v[36:37]
	v_cvt_pk_bf16_f32 v18, v18, v19
	v_cvt_pk_bf16_f32 v19, v20, v21
	v_cvt_pk_bf16_f32 v2, v2, v3
	v_cvt_pk_bf16_f32 v3, v4, v5
	v_pk_mul_f32 v[26:27], v[26:27], v[0:1] op_sel_hi:[1,0]
	v_pk_mul_f32 v[28:29], v[28:29], v[0:1] op_sel_hi:[1,0]
	v_pk_mul_f32 v[10:11], v[10:11], v[0:1] op_sel_hi:[1,0]
	v_pk_mul_f32 v[12:13], v[12:13], v[0:1] op_sel_hi:[1,0]
	global_store_dwordx2 v[34:35], v[18:19], off
	v_cvt_pk_bf16_f32 v18, v22, v23
	v_cvt_pk_bf16_f32 v19, v24, v25
	global_store_dwordx2 v[34:35], v[2:3], off offset:64
	v_cvt_pk_bf16_f32 v2, v6, v7
	v_cvt_pk_bf16_f32 v3, v8, v9
	v_pk_mul_f32 v[30:31], v[30:31], v[0:1] op_sel_hi:[1,0]
	v_pk_mul_f32 v[32:33], v[32:33], v[0:1] op_sel_hi:[1,0]
	v_pk_mul_f32 v[14:15], v[14:15], v[0:1] op_sel_hi:[1,0]
	v_pk_mul_f32 v[16:17], v[16:17], v[0:1] op_sel_hi:[1,0]
	global_store_dwordx2 v[34:35], v[18:19], off offset:16
	v_cvt_pk_bf16_f32 v18, v26, v27
	v_cvt_pk_bf16_f32 v19, v28, v29
	global_store_dwordx2 v[34:35], v[2:3], off offset:80
	v_cvt_pk_bf16_f32 v2, v10, v11
	v_cvt_pk_bf16_f32 v3, v12, v13
	global_store_dwordx2 v[34:35], v[18:19], off offset:32
	v_cvt_pk_bf16_f32 v18, v30, v31
	v_cvt_pk_bf16_f32 v19, v32, v33
	global_store_dwordx2 v[34:35], v[2:3], off offset:96
	v_cvt_pk_bf16_f32 v2, v14, v15
	v_cvt_pk_bf16_f32 v3, v16, v17
	s_mov_b64 s[10:11], 0
	global_store_dwordx2 v[34:35], v[18:19], off offset:48
	global_store_dwordx2 v[34:35], v[2:3], off offset:112

.LBB0_487:
	v_lshl_add_u64 v[66:67], v[166:167], 0, v[0:1]
	s_barrier
	s_waitcnt vmcnt(0)
	ds_write_b128 v185, v[134:137]
	ds_write_b128 v186, v[130:133]
	ds_write_b128 v187, v[126:129] offset:13312
	ds_write_b128 v188, v[122:125] offset:13312
	ds_write_b128 v189, v[118:121] offset:13312
	ds_write_b128 v190, v[114:117] offset:13312
	s_waitcnt lgkmcnt(0)
	s_barrier
	global_load_dwordx4 v[134:137], v[172:173], off
	global_load_dwordx4 v[130:133], v[168:169], off
	global_load_dwordx4 v[126:129], v[66:67], off
	v_lshl_add_u64 v[66:67], v[164:165], 0, v[0:1]
	global_load_dwordx4 v[122:125], v[66:67], off
	v_lshl_add_u64 v[66:67], v[162:163], 0, v[0:1]
	global_load_dwordx4 v[118:121], v[66:67], off
	v_lshl_add_u64 v[66:67], v[160:161], 0, v[0:1]
	global_load_dwordx4 v[114:117], v[66:67], off
	v_mov_b32_e32 v193, v180
	v_mov_b32_e32 v174, v184
	v_add_u32_e32 v192, v182, v183
	ds_read_b128 v[66:69], v192
	ds_read_b128 v[70:73], v181 offset:4608
	ds_read_b128 v[138:141], v181 offset:32
	ds_read_b128 v[142:145], v181 offset:4640
	ds_read_b128 v[236:239], v181 offset:64
	ds_read_b128 v[240:243], v181 offset:4672
	ds_read_b128 v[250:253], v181 offset:96
	s_waitcnt lgkmcnt(6)
	v_mfma_f32_32x32x16_bf16 v[82:97], v[66:69], v[110:113], 0
	s_waitcnt lgkmcnt(5)
	v_mfma_f32_32x32x16_bf16 v[66:81], v[70:73], v[110:113], 0
	s_waitcnt lgkmcnt(4)
	v_mfma_f32_32x32x16_bf16 v[82:97], v[138:141], v[106:109], v[82:97]
	ds_read_b128 v[138:141], v181 offset:4704
	s_waitcnt lgkmcnt(4)
	v_mfma_f32_32x32x16_bf16 v[66:81], v[142:145], v[106:109], v[66:81]
	s_waitcnt lgkmcnt(3)
	v_mfma_f32_32x32x16_bf16 v[82:97], v[236:239], v[102:105], v[82:97]
	s_waitcnt lgkmcnt(2)
	v_mfma_f32_32x32x16_bf16 v[66:81], v[240:243], v[102:105], v[66:81]
	s_waitcnt lgkmcnt(1)
	v_mfma_f32_32x32x16_bf16 v[82:97], v[250:253], v[98:101], v[82:97]
	s_waitcnt lgkmcnt(0)
	v_mfma_f32_32x32x16_bf16 v[66:81], v[138:141], v[98:101], v[66:81]
	s_nop 11
	v_max_f32_e32 v146, v66, v66
	v_max_f32_e32 v147, v82, v82
	v_max_f32_e32 v146, v147, v146
	v_max3_f32 v146, v146, v83, v67
	v_max3_f32 v146, v146, v84, v68
	v_max3_f32 v146, v146, v85, v69
	v_max3_f32 v146, v146, v86, v70
	v_max3_f32 v146, v146, v87, v71
	v_max3_f32 v146, v146, v88, v72
	v_max3_f32 v146, v146, v89, v73
	v_max3_f32 v146, v146, v90, v74
	v_max3_f32 v146, v146, v91, v75
	v_max3_f32 v146, v146, v92, v76
	v_max3_f32 v146, v146, v93, v77
	v_max3_f32 v146, v146, v94, v78
	v_max3_f32 v146, v146, v95, v79
	v_max3_f32 v146, v146, v96, v80
	v_max3_f32 v180, v146, v97, v81
	ds_bpermute_b32 v184, v155, v180
	v_add_u32_e32 v176, 0x3000, v191
	v_add_u32_e32 v177, 0x4000, v191
	v_add_u32_e32 v179, 0x5800, v191
	v_add_u32_e32 v178, 0x6800, v191
	s_waitcnt lgkmcnt(0)
	v_max_f32_e32 v184, v184, v184
	v_max_f32_e32 v180, v180, v184
	v_mul_f32_e32 v180, 0x3e38aa3b, v180
	v_max_f32_e32 v184, v174, v174
	v_max_f32_e32 v184, v184, v180
	v_sub_f32_e32 v174, v174, v184
	v_fma_f32 v82, v82, s27, -v184
	v_exp_f32_e32 v174, v174
	v_exp_f32_e32 v82, v82
	v_fma_f32 v83, v83, s27, -v184
	ds_read2_b64 v[138:141], v176 offset0:128 offset1:130
	ds_read2_b64 v[142:145], v177 offset0:192 offset1:194
	ds_read2_b64 v[150:153], v179 offset1:2
	ds_read2_b64 v[146:149], v178 offset0:64 offset1:66
	v_exp_f32_e32 v83, v83
	s_nop 0
	s_nop 0
	v_fma_f32 v84, v84, s27, -v184
	v_add_f32_e32 v180, 0, v82
	v_fma_f32 v66, v66, s27, -v184
	s_nop 0
	v_exp_f32_e32 v84, v84
	v_fma_f32 v85, v85, s27, -v184
	v_add_f32_e32 v180, v180, v83
	v_exp_f32_e32 v219, v66
	v_fma_f32 v66, v67, s27, -v184
	v_exp_f32_e32 v85, v85
	s_nop 0
	v_fma_f32 v86, v86, s27, -v184
	v_add_f32_e32 v180, v180, v84
	v_exp_f32_e32 v220, v66
	v_fma_f32 v66, v68, s27, -v184
	s_nop 0
	v_exp_f32_e32 v86, v86
	v_fma_f32 v87, v87, s27, -v184
	v_add_f32_e32 v180, v180, v85
	v_exp_f32_e32 v221, v66
	v_fma_f32 v66, v69, s27, -v184
	v_exp_f32_e32 v87, v87
	s_nop 0
	v_fma_f32 v88, v88, s27, -v184
	v_add_f32_e32 v180, v180, v86
	v_exp_f32_e32 v222, v66
	v_fma_f32 v66, v70, s27, -v184
	s_nop 0
	v_exp_f32_e32 v88, v88
	v_fma_f32 v89, v89, s27, -v184
	v_add_f32_e32 v180, v180, v87
	v_fma_f32 v90, v90, s27, -v184
	v_exp_f32_e32 v223, v66
	v_fma_f32 v66, v71, s27, -v184
	v_exp_f32_e32 v89, v89
	s_nop 0
	v_exp_f32_e32 v211, v90
	v_add_f32_e32 v180, v180, v88
	v_fma_f32 v90, v91, s27, -v184
	v_exp_f32_e32 v224, v66
	v_fma_f32 v66, v72, s27, -v184
	s_nop 0
	v_exp_f32_e32 v212, v90
	v_add_f32_e32 v90, v180, v89
	v_exp_f32_e32 v225, v66
	v_fma_f32 v66, v73, s27, -v184
	s_nop 0
	v_fma_f32 v91, v92, s27, -v184
	v_add_f32_e32 v90, v90, v211
	v_exp_f32_e32 v226, v66
	v_fma_f32 v66, v74, s27, -v184
	s_nop 0
	v_exp_f32_e32 v213, v91
	v_fma_f32 v91, v93, s27, -v184
	v_add_f32_e32 v90, v90, v212
	v_exp_f32_e32 v227, v66
	v_fma_f32 v66, v75, s27, -v184
	v_exp_f32_e32 v214, v91
	s_nop 0
	v_fma_f32 v91, v94, s27, -v184
	v_add_f32_e32 v90, v90, v213
	v_exp_f32_e32 v228, v66
	v_fma_f32 v66, v76, s27, -v184
	s_nop 0
	v_exp_f32_e32 v215, v91
	v_fma_f32 v91, v95, s27, -v184
	v_add_f32_e32 v90, v90, v214
	v_exp_f32_e32 v229, v66
	v_fma_f32 v66, v77, s27, -v184
	v_exp_f32_e32 v216, v91
	s_nop 0
	v_fma_f32 v91, v96, s27, -v184
	v_add_f32_e32 v90, v90, v215
	v_exp_f32_e32 v230, v66
	v_fma_f32 v66, v78, s27, -v184
	s_nop 0
	v_exp_f32_e32 v217, v91
	v_fma_f32 v91, v97, s27, -v184
	v_add_f32_e32 v90, v90, v216
	v_exp_f32_e32 v231, v66
	v_fma_f32 v66, v79, s27, -v184
	v_exp_f32_e32 v218, v91
	s_nop 0
	v_exp_f32_e32 v232, v66
	v_add_f32_e32 v90, v90, v217
	v_fma_f32 v66, v80, s27, -v184
	s_nop 0
	v_exp_f32_e32 v233, v66
	v_add_f32_e32 v90, v90, v218
	v_fma_f32 v66, v81, s27, -v184
	s_nop 0
	v_exp_f32_e32 v234, v66
	v_add_f32_e32 v66, v90, v219
	s_nop 0
	s_nop 0
	s_nop 0
	s_nop 0
	s_nop 0
	s_nop 0
	s_nop 0
	v_add_f32_e32 v66, v66, v220
	v_add_f32_e32 v66, v66, v221
	v_add_f32_e32 v66, v66, v222
	v_add_f32_e32 v66, v66, v223
	v_add_f32_e32 v66, v66, v224
	v_add_f32_e32 v66, v66, v225
	s_nop 0
	s_nop 0
	s_nop 0
	s_nop 0
	s_nop 0
	s_nop 0
	s_nop 0
	v_add_f32_e32 v66, v66, v226
	v_add_f32_e32 v66, v66, v227
	v_add_f32_e32 v66, v66, v228
	v_add_f32_e32 v66, v66, v229
	v_add_f32_e32 v66, v66, v230
	v_add_f32_e32 v66, v66, v231
	s_nop 0
	s_nop 0
	s_nop 0
	v_pk_mul_f32 v[64:65], v[64:65], v[174:175] op_sel_hi:[1,0]
	v_add_f32_e32 v66, v66, v232
	v_add_f32_e32 v66, v66, v233
	v_add_f32_e32 v180, v66, v234
	ds_read2_b64 v[66:69], v176 offset0:132 offset1:134
	ds_read2_b64 v[70:73], v177 offset0:196 offset1:198
	ds_read2_b64 v[74:77], v179 offset0:4 offset1:6
	ds_read2_b64 v[78:81], v178 offset0:68 offset1:70
	v_pk_mul_f32 v[62:63], v[62:63], v[174:175] op_sel_hi:[1,0]
	v_pk_mul_f32 v[60:61], v[60:61], v[174:175] op_sel_hi:[1,0]
	v_pk_mul_f32 v[58:59], v[58:59], v[174:175] op_sel_hi:[1,0]
	v_pk_mul_f32 v[56:57], v[56:57], v[174:175] op_sel_hi:[1,0]
	v_pk_mul_f32 v[54:55], v[54:55], v[174:175] op_sel_hi:[1,0]
	v_pk_mul_f32 v[52:53], v[52:53], v[174:175] op_sel_hi:[1,0]
	v_pk_mul_f32 v[50:51], v[50:51], v[174:175] op_sel_hi:[1,0]
	v_pk_mul_f32 v[48:49], v[48:49], v[174:175] op_sel_hi:[1,0]
	v_pk_mul_f32 v[46:47], v[46:47], v[174:175] op_sel_hi:[1,0]
	v_pk_mul_f32 v[44:45], v[44:45], v[174:175] op_sel_hi:[1,0]
	v_pk_mul_f32 v[42:43], v[42:43], v[174:175] op_sel_hi:[1,0]
	v_pk_mul_f32 v[40:41], v[40:41], v[174:175] op_sel_hi:[1,0]
	v_pk_mul_f32 v[38:39], v[38:39], v[174:175] op_sel_hi:[1,0]
	v_pk_mul_f32 v[36:37], v[36:37], v[174:175] op_sel_hi:[1,0]
	v_pk_mul_f32 v[34:35], v[34:35], v[174:175] op_sel_hi:[1,0]
	v_pk_mul_f32 v[32:33], v[32:33], v[174:175] op_sel_hi:[1,0]
	v_pk_mul_f32 v[30:31], v[30:31], v[174:175] op_sel_hi:[1,0]
	v_pk_mul_f32 v[28:29], v[28:29], v[174:175] op_sel_hi:[1,0]
	v_pk_mul_f32 v[26:27], v[26:27], v[174:175] op_sel_hi:[1,0]
	v_pk_mul_f32 v[24:25], v[24:25], v[174:175] op_sel_hi:[1,0]
	v_pk_mul_f32 v[22:23], v[22:23], v[174:175] op_sel_hi:[1,0]
	v_pk_mul_f32 v[20:21], v[20:21], v[174:175] op_sel_hi:[1,0]
	v_pk_mul_f32 v[18:19], v[18:19], v[174:175] op_sel_hi:[1,0]
	v_pk_mul_f32 v[16:17], v[16:17], v[174:175] op_sel_hi:[1,0]
	v_pk_mul_f32 v[14:15], v[14:15], v[174:175] op_sel_hi:[1,0]
	v_pk_mul_f32 v[12:13], v[12:13], v[174:175] op_sel_hi:[1,0]
	v_pk_mul_f32 v[10:11], v[10:11], v[174:175] op_sel_hi:[1,0]
	v_pk_mul_f32 v[8:9], v[8:9], v[174:175] op_sel_hi:[1,0]
	v_pk_mul_f32 v[6:7], v[6:7], v[174:175] op_sel_hi:[1,0]
	v_pk_mul_f32 v[4:5], v[4:5], v[174:175] op_sel_hi:[1,0]
	v_pk_mul_f32 v[2:3], v[2:3], v[174:175] op_sel_hi:[1,0]
	v_cvt_pk_bf16_f32 v82, v82, v83
	v_cvt_pk_bf16_f32 v83, v84, v85
	v_cvt_pk_bf16_f32 v84, v86, v87
	v_cvt_pk_bf16_f32 v85, v88, v89
	s_waitcnt lgkmcnt(7)
	s_nop 0
	v_mfma_f32_32x32x16_bf16 v[50:65], v[138:141], v[82:85], v[50:65]
	s_waitcnt lgkmcnt(6)
	v_mfma_f32_32x32x16_bf16 v[34:49], v[142:145], v[82:85], v[34:49]
	s_waitcnt lgkmcnt(5)
	v_mfma_f32_32x32x16_bf16 v[18:33], v[150:153], v[82:85], v[18:33]
	s_waitcnt lgkmcnt(4)
	v_mfma_f32_32x32x16_bf16 v[2:17], v[146:149], v[82:85], v[2:17]
	ds_read2_b64 v[82:85], v176 offset0:136 offset1:138
	ds_read2_b64 v[86:89], v177 offset0:200 offset1:202
	ds_read2_b64 v[90:93], v179 offset0:8 offset1:10
	ds_read2_b64 v[94:97], v178 offset0:72 offset1:74
	v_cvt_pk_bf16_f32 v138, v211, v212
	v_cvt_pk_bf16_f32 v139, v213, v214
	v_cvt_pk_bf16_f32 v140, v215, v216
	v_cvt_pk_bf16_f32 v141, v217, v218
	s_waitcnt lgkmcnt(7)
	s_nop 0
	v_mfma_f32_32x32x16_bf16 v[50:65], v[66:69], v[138:141], v[50:65]
	s_waitcnt lgkmcnt(6)
	v_mfma_f32_32x32x16_bf16 v[34:49], v[70:73], v[138:141], v[34:49]
	s_waitcnt lgkmcnt(5)
	v_mfma_f32_32x32x16_bf16 v[18:33], v[74:77], v[138:141], v[18:33]
	s_waitcnt lgkmcnt(4)
	v_mfma_f32_32x32x16_bf16 v[2:17], v[78:81], v[138:141], v[2:17]
	ds_read2_b64 v[66:69], v176 offset0:140 offset1:142
	ds_read2_b64 v[70:73], v177 offset0:204 offset1:206
	ds_read2_b64 v[74:77], v179 offset0:12 offset1:14
	ds_read2_b64 v[78:81], v178 offset0:76 offset1:78
	v_cvt_pk_bf16_f32 v138, v219, v220
	v_cvt_pk_bf16_f32 v139, v221, v222
	v_cvt_pk_bf16_f32 v140, v223, v224
	v_cvt_pk_bf16_f32 v141, v225, v226
	s_waitcnt lgkmcnt(7)
	s_nop 0
	v_mfma_f32_32x32x16_bf16 v[50:65], v[82:85], v[138:141], v[50:65]
	s_waitcnt lgkmcnt(6)
	v_mfma_f32_32x32x16_bf16 v[34:49], v[86:89], v[138:141], v[34:49]
	s_waitcnt lgkmcnt(5)
	v_mfma_f32_32x32x16_bf16 v[18:33], v[90:93], v[138:141], v[18:33]
	s_waitcnt lgkmcnt(4)
	v_mfma_f32_32x32x16_bf16 v[2:17], v[94:97], v[138:141], v[2:17]
	v_cvt_pk_bf16_f32 v82, v227, v228
	v_cvt_pk_bf16_f32 v83, v229, v230
	v_cvt_pk_bf16_f32 v84, v231, v232
	v_cvt_pk_bf16_f32 v85, v233, v234
	s_waitcnt lgkmcnt(3)
	s_nop 0
	v_mfma_f32_32x32x16_bf16 v[50:65], v[66:69], v[82:85], v[50:65]
	s_waitcnt lgkmcnt(2)
	v_mfma_f32_32x32x16_bf16 v[34:49], v[70:73], v[82:85], v[34:49]
	s_waitcnt lgkmcnt(1)
	v_mfma_f32_32x32x16_bf16 v[18:33], v[74:77], v[82:85], v[18:33]
	s_waitcnt lgkmcnt(0)
	v_mfma_f32_32x32x16_bf16 v[2:17], v[78:81], v[82:85], v[2:17]
	s_add_i32 s18, s18, -1
	v_fmac_f32_e32 v180, v193, v174
	v_lshl_add_u64 v[160:161], v[160:161], 0, s[36:37]
	v_lshl_add_u64 v[162:163], v[162:163], 0, s[36:37]
	v_lshl_add_u64 v[164:165], v[164:165], 0, s[36:37]
	v_lshl_add_u64 v[166:167], v[166:167], 0, s[36:37]
	v_lshl_add_u64 v[168:169], v[168:169], 0, s[38:39]
	s_cmp_lg_u32 s18, 0
	v_lshl_add_u64 v[172:173], v[172:173], 0, s[38:39]
	s_cbranch_scc1 .LBB0_487
	s_barrier
	s_waitcnt vmcnt(5)
	ds_write_b128 v185, v[134:137]
	s_waitcnt vmcnt(4)
	ds_write_b128 v186, v[130:133]
	s_waitcnt vmcnt(3)
	ds_write_b128 v187, v[126:129] offset:13312
	s_waitcnt vmcnt(2)
	ds_write_b128 v188, v[122:125] offset:13312
	s_waitcnt vmcnt(1)
	ds_write_b128 v189, v[118:121] offset:13312
	s_waitcnt vmcnt(0)
	ds_write_b128 v190, v[114:117] offset:13312
	s_waitcnt lgkmcnt(0)
	s_barrier
	ds_read_b128 v[66:69], v192
	ds_read_b128 v[70:73], v181 offset:4608
	s_waitcnt lgkmcnt(1)
	v_mfma_f32_32x32x16_bf16 v[82:97], v[66:69], v[110:113], 0
	ds_read_b128 v[114:117], v181 offset:32
	s_waitcnt lgkmcnt(1)
	v_mfma_f32_32x32x16_bf16 v[66:81], v[70:73], v[110:113], 0
	ds_read_b128 v[110:113], v181 offset:4640
	s_waitcnt lgkmcnt(1)
	v_mfma_f32_32x32x16_bf16 v[82:97], v[114:117], v[106:109], v[82:97]
	ds_read_b128 v[114:117], v181 offset:64
	s_waitcnt lgkmcnt(1)
	v_mfma_f32_32x32x16_bf16 v[66:81], v[110:113], v[106:109], v[66:81]
	ds_read_b128 v[106:109], v181 offset:4672
	s_waitcnt lgkmcnt(1)
	v_mfma_f32_32x32x16_bf16 v[82:97], v[114:117], v[102:105], v[82:97]
	ds_read_b128 v[110:113], v181 offset:96
	s_waitcnt lgkmcnt(1)
	v_mfma_f32_32x32x16_bf16 v[66:81], v[106:109], v[102:105], v[66:81]
	ds_read_b128 v[102:105], v181 offset:4704
	s_waitcnt lgkmcnt(1)
	v_mfma_f32_32x32x16_bf16 v[82:97], v[110:113], v[98:101], v[82:97]
	s_waitcnt lgkmcnt(0)
	v_mfma_f32_32x32x16_bf16 v[66:81], v[102:105], v[98:101], v[66:81]
	s_nop 11
	v_max_f32_e32 v0, v66, v66
	v_max_f32_e32 v98, v82, v82
	v_max_f32_e32 v0, v98, v0
	v_max3_f32 v0, v0, v83, v67
	v_max3_f32 v0, v0, v84, v68
	v_max3_f32 v0, v0, v85, v69
	v_max3_f32 v0, v0, v86, v70
	v_max3_f32 v0, v0, v87, v71
	v_max3_f32 v0, v0, v88, v72
	v_max3_f32 v0, v0, v89, v73
	v_max3_f32 v0, v0, v90, v74
	v_max3_f32 v0, v0, v91, v75
	v_max3_f32 v0, v0, v92, v76
	v_max3_f32 v0, v0, v93, v77
	v_max3_f32 v0, v0, v94, v78
	v_max3_f32 v0, v0, v95, v79
	v_max3_f32 v0, v0, v96, v80
	v_max3_f32 v0, v0, v97, v81
	ds_bpermute_b32 v106, v155, v0
	v_max_f32_e32 v107, v184, v184
	ds_read2_b64 v[102:105], v176 offset0:128 offset1:130
	ds_read2_b64 v[98:101], v177 offset0:192 offset1:194
	s_waitcnt lgkmcnt(2)
	v_max_f32_e32 v106, v106, v106
	v_max_f32_e32 v0, v0, v106
	v_mul_f32_e32 v0, 0x3e38aa3b, v0
	v_max_f32_e32 v114, v107, v0
	v_fma_f32 v82, v82, s27, -v114
	v_fma_f32 v66, v66, s27, -v114
	v_exp_f32_e32 v115, v82
	v_fma_f32 v82, v83, s27, -v114
	v_exp_f32_e32 v131, v66
	v_fma_f32 v66, v67, s27, -v114
	v_exp_f32_e32 v116, v82
	v_fma_f32 v82, v84, s27, -v114
	v_exp_f32_e32 v132, v66
	v_fma_f32 v66, v68, s27, -v114
	v_exp_f32_e32 v117, v82
	v_fma_f32 v82, v85, s27, -v114
	v_exp_f32_e32 v133, v66
	v_fma_f32 v66, v69, s27, -v114
	v_exp_f32_e32 v118, v82
	v_fma_f32 v82, v86, s27, -v114
	v_exp_f32_e32 v134, v66
	v_fma_f32 v66, v70, s27, -v114
	v_exp_f32_e32 v119, v82
	v_fma_f32 v82, v87, s27, -v114
	v_exp_f32_e32 v135, v66
	v_fma_f32 v66, v71, s27, -v114
	v_exp_f32_e32 v120, v82
	v_fma_f32 v82, v88, s27, -v114
	v_exp_f32_e32 v136, v66
	v_fma_f32 v66, v72, s27, -v114
	v_exp_f32_e32 v121, v82
	v_fma_f32 v82, v89, s27, -v114
	v_exp_f32_e32 v137, v66
	v_fma_f32 v66, v73, s27, -v114
	v_exp_f32_e32 v122, v82
	v_fma_f32 v82, v90, s27, -v114
	v_exp_f32_e32 v138, v66
	v_fma_f32 v66, v74, s27, -v114
	v_exp_f32_e32 v123, v82
	v_fma_f32 v82, v91, s27, -v114
	v_exp_f32_e32 v139, v66
	v_fma_f32 v66, v75, s27, -v114
	v_exp_f32_e32 v124, v82
	v_fma_f32 v82, v92, s27, -v114
	v_exp_f32_e32 v140, v66
	v_fma_f32 v66, v76, s27, -v114
	v_exp_f32_e32 v125, v82
	v_fma_f32 v82, v93, s27, -v114
	v_exp_f32_e32 v141, v66
	v_fma_f32 v66, v77, s27, -v114
	v_exp_f32_e32 v126, v82
	v_fma_f32 v82, v94, s27, -v114
	v_exp_f32_e32 v142, v66
	v_fma_f32 v66, v78, s27, -v114
	v_exp_f32_e32 v127, v82
	v_fma_f32 v82, v95, s27, -v114
	v_exp_f32_e32 v143, v66
	v_fma_f32 v66, v79, s27, -v114
	v_exp_f32_e32 v128, v82
	v_fma_f32 v82, v96, s27, -v114
	v_exp_f32_e32 v144, v66
	v_fma_f32 v66, v80, s27, -v114
	v_sub_f32_e32 v0, v184, v114
	v_exp_f32_e32 v129, v82
	v_fma_f32 v82, v97, s27, -v114
	v_exp_f32_e32 v145, v66
	v_fma_f32 v66, v81, s27, -v114
	v_exp_f32_e32 v0, v0
	v_exp_f32_e32 v130, v82
	v_exp_f32_e32 v114, v66
	ds_read2_b64 v[110:113], v179 offset1:2
	ds_read2_b64 v[106:109], v178 offset0:64 offset1:66
	s_nop 0
	s_nop 0
	s_nop 0
	s_nop 0
	s_nop 0
	s_nop 0
	s_nop 0
	s_nop 0
	s_nop 0
	s_nop 0
	s_nop 0
	s_nop 0
	s_nop 0
	s_nop 0
	s_nop 0
	s_nop 0
	s_nop 0
	s_nop 0
	s_nop 0
	s_nop 0
	s_nop 0
	s_nop 0
	s_nop 0
	s_nop 0
	s_nop 0
	s_nop 0
	s_nop 0
	s_nop 0
	s_nop 0
	s_nop 0
	s_nop 0
	s_nop 0
	s_nop 0
	ds_read2_b64 v[66:69], v176 offset0:132 offset1:134
	ds_read2_b64 v[70:73], v177 offset0:196 offset1:198
	ds_read2_b64 v[74:77], v179 offset0:4 offset1:6
	ds_read2_b64 v[78:81], v178 offset0:68 offset1:70
	v_pk_mul_f32 v[60:61], v[60:61], v[0:1] op_sel_hi:[1,0]
	v_pk_mul_f32 v[58:59], v[58:59], v[0:1] op_sel_hi:[1,0]
	v_pk_mul_f32 v[56:57], v[56:57], v[0:1] op_sel_hi:[1,0]
	v_pk_mul_f32 v[54:55], v[54:55], v[0:1] op_sel_hi:[1,0]
	v_pk_mul_f32 v[52:53], v[52:53], v[0:1] op_sel_hi:[1,0]
	v_pk_mul_f32 v[50:51], v[50:51], v[0:1] op_sel_hi:[1,0]
	v_pk_mul_f32 v[48:49], v[48:49], v[0:1] op_sel_hi:[1,0]
	v_pk_mul_f32 v[46:47], v[46:47], v[0:1] op_sel_hi:[1,0]
	v_pk_mul_f32 v[44:45], v[44:45], v[0:1] op_sel_hi:[1,0]
	v_pk_mul_f32 v[42:43], v[42:43], v[0:1] op_sel_hi:[1,0]
	v_pk_mul_f32 v[40:41], v[40:41], v[0:1] op_sel_hi:[1,0]
	v_pk_mul_f32 v[38:39], v[38:39], v[0:1] op_sel_hi:[1,0]
	v_pk_mul_f32 v[36:37], v[36:37], v[0:1] op_sel_hi:[1,0]
	v_pk_mul_f32 v[34:35], v[34:35], v[0:1] op_sel_hi:[1,0]
	v_pk_mul_f32 v[28:29], v[28:29], v[0:1] op_sel_hi:[1,0]
	v_pk_mul_f32 v[26:27], v[26:27], v[0:1] op_sel_hi:[1,0]
	v_pk_mul_f32 v[24:25], v[24:25], v[0:1] op_sel_hi:[1,0]
	v_pk_mul_f32 v[22:23], v[22:23], v[0:1] op_sel_hi:[1,0]
	v_pk_mul_f32 v[20:21], v[20:21], v[0:1] op_sel_hi:[1,0]
	v_pk_mul_f32 v[18:19], v[18:19], v[0:1] op_sel_hi:[1,0]
	v_pk_mul_f32 v[12:13], v[12:13], v[0:1] op_sel_hi:[1,0]
	v_pk_mul_f32 v[10:11], v[10:11], v[0:1] op_sel_hi:[1,0]
	v_pk_mul_f32 v[8:9], v[8:9], v[0:1] op_sel_hi:[1,0]
	v_pk_mul_f32 v[6:7], v[6:7], v[0:1] op_sel_hi:[1,0]
	v_pk_mul_f32 v[4:5], v[4:5], v[0:1] op_sel_hi:[1,0]
	v_pk_mul_f32 v[2:3], v[2:3], v[0:1] op_sel_hi:[1,0]
	v_pk_mul_f32 v[64:65], v[64:65], v[0:1] op_sel_hi:[1,0]
	v_pk_mul_f32 v[62:63], v[62:63], v[0:1] op_sel_hi:[1,0]
	v_pk_mul_f32 v[32:33], v[32:33], v[0:1] op_sel_hi:[1,0]
	v_pk_mul_f32 v[30:31], v[30:31], v[0:1] op_sel_hi:[1,0]
	v_pk_mul_f32 v[16:17], v[16:17], v[0:1] op_sel_hi:[1,0]
	v_pk_mul_f32 v[14:15], v[14:15], v[0:1] op_sel_hi:[1,0]
	v_cvt_pk_bf16_f32 v82, v115, v116
	v_cvt_pk_bf16_f32 v83, v117, v118
	v_cvt_pk_bf16_f32 v84, v119, v120
	v_cvt_pk_bf16_f32 v85, v121, v122
	s_waitcnt lgkmcnt(7)
	s_nop 0
	v_mfma_f32_32x32x16_bf16 v[50:65], v[102:105], v[82:85], v[50:65]
	s_waitcnt lgkmcnt(6)
	v_mfma_f32_32x32x16_bf16 v[34:49], v[98:101], v[82:85], v[34:49]
	s_waitcnt lgkmcnt(5)
	v_mfma_f32_32x32x16_bf16 v[18:33], v[110:113], v[82:85], v[18:33]
	s_waitcnt lgkmcnt(4)
	v_mfma_f32_32x32x16_bf16 v[2:17], v[106:109], v[82:85], v[2:17]
	ds_read2_b64 v[82:85], v176 offset0:136 offset1:138
	ds_read2_b64 v[86:89], v177 offset0:200 offset1:202
	ds_read2_b64 v[90:93], v179 offset0:8 offset1:10
	ds_read2_b64 v[94:97], v178 offset0:72 offset1:74
	v_cvt_pk_bf16_f32 v98, v123, v124
	v_cvt_pk_bf16_f32 v99, v125, v126
	v_cvt_pk_bf16_f32 v100, v127, v128
	v_cvt_pk_bf16_f32 v101, v129, v130
	s_waitcnt lgkmcnt(7)
	s_nop 0
	v_mfma_f32_32x32x16_bf16 v[50:65], v[66:69], v[98:101], v[50:65]
	s_waitcnt lgkmcnt(6)
	v_mfma_f32_32x32x16_bf16 v[34:49], v[70:73], v[98:101], v[34:49]
	s_waitcnt lgkmcnt(5)
	v_mfma_f32_32x32x16_bf16 v[18:33], v[74:77], v[98:101], v[18:33]
	s_waitcnt lgkmcnt(4)
	v_mfma_f32_32x32x16_bf16 v[2:17], v[78:81], v[98:101], v[2:17]
	ds_read2_b64 v[66:69], v176 offset0:140 offset1:142
	ds_read2_b64 v[70:73], v177 offset0:204 offset1:206
	ds_read2_b64 v[74:77], v179 offset0:12 offset1:14
	ds_read2_b64 v[78:81], v178 offset0:76 offset1:78
	v_cvt_pk_bf16_f32 v98, v131, v132
	v_cvt_pk_bf16_f32 v99, v133, v134
	v_cvt_pk_bf16_f32 v100, v135, v136
	v_cvt_pk_bf16_f32 v101, v137, v138
	s_waitcnt lgkmcnt(7)
	s_nop 0
	v_mfma_f32_32x32x16_bf16 v[50:65], v[82:85], v[98:101], v[50:65]
	s_waitcnt lgkmcnt(6)
	v_mfma_f32_32x32x16_bf16 v[34:49], v[86:89], v[98:101], v[34:49]
	s_waitcnt lgkmcnt(5)
	v_mfma_f32_32x32x16_bf16 v[18:33], v[90:93], v[98:101], v[18:33]
	s_waitcnt lgkmcnt(4)
	v_mfma_f32_32x32x16_bf16 v[2:17], v[94:97], v[98:101], v[2:17]
	v_cvt_pk_bf16_f32 v82, v139, v140
	v_cvt_pk_bf16_f32 v83, v141, v142
	v_cvt_pk_bf16_f32 v84, v143, v144
	v_cvt_pk_bf16_f32 v85, v145, v114
	s_waitcnt lgkmcnt(3)
	s_nop 0
	v_mfma_f32_32x32x16_bf16 v[50:65], v[66:69], v[82:85], v[50:65]
	s_waitcnt lgkmcnt(2)
	v_mfma_f32_32x32x16_bf16 v[34:49], v[70:73], v[82:85], v[34:49]
	s_waitcnt lgkmcnt(1)
	v_mfma_f32_32x32x16_bf16 v[18:33], v[74:77], v[82:85], v[18:33]
	s_waitcnt lgkmcnt(0)
	v_mfma_f32_32x32x16_bf16 v[2:17], v[78:81], v[82:85], v[2:17]
	v_add_f32_e32 v66, 0, v115
	v_add_f32_e32 v66, v66, v116
	v_add_f32_e32 v66, v66, v117
	v_add_f32_e32 v66, v66, v118
	v_add_f32_e32 v66, v66, v119
	v_add_f32_e32 v66, v66, v120
	v_add_f32_e32 v66, v66, v121
	v_add_f32_e32 v66, v66, v122
	v_add_f32_e32 v66, v66, v123
	v_add_f32_e32 v66, v66, v124
	v_add_f32_e32 v66, v66, v125
	v_add_f32_e32 v66, v66, v126
	v_add_f32_e32 v66, v66, v127
	v_add_f32_e32 v66, v66, v128
	v_add_f32_e32 v66, v66, v129
	v_add_f32_e32 v66, v66, v130
	v_add_f32_e32 v66, v66, v131
	v_add_f32_e32 v66, v66, v132
	v_add_f32_e32 v66, v66, v133
	v_add_f32_e32 v66, v66, v134
	v_add_f32_e32 v66, v66, v135
	v_add_f32_e32 v66, v66, v136
	v_add_f32_e32 v66, v66, v137
	v_add_f32_e32 v66, v66, v138
	v_add_f32_e32 v66, v66, v139
	v_add_f32_e32 v66, v66, v140
	v_add_f32_e32 v66, v66, v141
	v_add_f32_e32 v66, v66, v142
	v_add_f32_e32 v66, v66, v143
	v_add_f32_e32 v66, v66, v144
	v_add_f32_e32 v66, v66, v145
	v_add_f32_e32 v66, v66, v114
	v_fmac_f32_e32 v66, v180, v0
	ds_bpermute_b32 v0, v155, v66
	s_mov_b64 s[20:21], -1
	s_waitcnt lgkmcnt(0)
	v_add_f32_e32 v0, v66, v0
	v_div_scale_f32 v66, s[18:19], v0, v0, 1.0
	v_rcp_f32_e32 v67, v66
	v_div_scale_f32 v68, vcc, 1.0, v0, 1.0
	v_fma_f32 v69, -v66, v67, 1.0
	v_fmac_f32_e32 v67, v69, v67
	v_mul_f32_e32 v69, v68, v67
	v_fma_f32 v70, -v66, v69, v68
	v_fmac_f32_e32 v69, v70, v67
	v_fma_f32 v66, -v66, v69, v68
	v_div_fmas_f32 v66, v66, v67, v69
	v_div_fixup_f32 v0, v66, v0, 1.0
	v_pk_mul_f32 v[74:75], v[50:51], v[0:1] op_sel_hi:[1,0]
	v_pk_mul_f32 v[76:77], v[52:53], v[0:1] op_sel_hi:[1,0]
	v_pk_mul_f32 v[70:71], v[54:55], v[0:1] op_sel_hi:[1,0]
	v_pk_mul_f32 v[72:73], v[56:57], v[0:1] op_sel_hi:[1,0]
	v_pk_mul_f32 v[66:67], v[58:59], v[0:1] op_sel_hi:[1,0]
	v_pk_mul_f32 v[68:69], v[60:61], v[0:1] op_sel_hi:[1,0]
	v_pk_mul_f32 v[58:59], v[62:63], v[0:1] op_sel_hi:[1,0]
	v_pk_mul_f32 v[60:61], v[64:65], v[0:1] op_sel_hi:[1,0]
	v_pk_mul_f32 v[54:55], v[34:35], v[0:1] op_sel_hi:[1,0]
	v_pk_mul_f32 v[56:57], v[36:37], v[0:1] op_sel_hi:[1,0]
	v_pk_mul_f32 v[50:51], v[38:39], v[0:1] op_sel_hi:[1,0]
	v_pk_mul_f32 v[52:53], v[40:41], v[0:1] op_sel_hi:[1,0]
	v_pk_mul_f32 v[42:43], v[42:43], v[0:1] op_sel_hi:[1,0]
	v_pk_mul_f32 v[44:45], v[44:45], v[0:1] op_sel_hi:[1,0]
	v_pk_mul_f32 v[46:47], v[46:47], v[0:1] op_sel_hi:[1,0]
	v_pk_mul_f32 v[48:49], v[48:49], v[0:1] op_sel_hi:[1,0]
	v_pk_mul_f32 v[34:35], v[18:19], v[0:1] op_sel_hi:[1,0]
	v_pk_mul_f32 v[36:37], v[20:21], v[0:1] op_sel_hi:[1,0]
	v_pk_mul_f32 v[38:39], v[22:23], v[0:1] op_sel_hi:[1,0]
	v_pk_mul_f32 v[40:41], v[24:25], v[0:1] op_sel_hi:[1,0]
	v_pk_mul_f32 v[18:19], v[26:27], v[0:1] op_sel_hi:[1,0]
	v_pk_mul_f32 v[20:21], v[28:29], v[0:1] op_sel_hi:[1,0]
	v_pk_mul_f32 v[22:23], v[30:31], v[0:1] op_sel_hi:[1,0]
	v_pk_mul_f32 v[24:25], v[32:33], v[0:1] op_sel_hi:[1,0]
	v_pk_mul_f32 v[26:27], v[2:3], v[0:1] op_sel_hi:[1,0]
	v_pk_mul_f32 v[28:29], v[4:5], v[0:1] op_sel_hi:[1,0]
	v_pk_mul_f32 v[2:3], v[6:7], v[0:1] op_sel_hi:[1,0]
	v_pk_mul_f32 v[4:5], v[8:9], v[0:1] op_sel_hi:[1,0]
	v_pk_mul_f32 v[10:11], v[10:11], v[0:1] op_sel_hi:[1,0]
	v_pk_mul_f32 v[12:13], v[12:13], v[0:1] op_sel_hi:[1,0]
	v_pk_mul_f32 v[6:7], v[14:15], v[0:1] op_sel_hi:[1,0]
	v_pk_mul_f32 v[8:9], v[16:17], v[0:1] op_sel_hi:[1,0]
	s_andn2_b64 vcc, exec, s[42:43]
	s_cbranch_vccnz .LBB0_485
	s_mov_b64 s[20:21], 0
	global_store_dwordx4 v[158:159], v[74:77], off
	global_store_dwordx4 v[158:159], v[70:73], off offset:16
	global_store_dwordx4 v[158:159], v[66:69], off offset:32
	global_store_dwordx4 v[158:159], v[58:61], off offset:48
	global_store_dwordx4 v[158:159], v[54:57], off offset:64
	global_store_dwordx4 v[158:159], v[50:53], off offset:80
	global_store_dwordx4 v[158:159], v[42:45], off offset:96
	global_store_dwordx4 v[158:159], v[46:49], off offset:112
	global_store_dwordx4 v[158:159], v[34:37], off offset:128
	global_store_dwordx4 v[158:159], v[38:41], off offset:144
	global_store_dwordx4 v[158:159], v[18:21], off offset:160
	global_store_dwordx4 v[158:159], v[22:25], off offset:176
	global_store_dwordx4 v[158:159], v[26:29], off offset:192
	global_store_dwordx4 v[158:159], v[2:5], off offset:208
	global_store_dwordx4 v[158:159], v[10:13], off offset:224
	global_store_dwordx4 v[158:159], v[6:9], off offset:240
	s_branch .LBB0_485

	.amdhsa_kernel _Z4mega6Paramsii
		.amdhsa_group_segment_fixed_size 16
		.amdhsa_private_segment_fixed_size 0
		.amdhsa_kernarg_size 3688
		.amdhsa_user_sgpr_count 2
		.amdhsa_user_sgpr_dispatch_ptr 0
		.amdhsa_user_sgpr_queue_ptr 0
		.amdhsa_user_sgpr_kernarg_segment_ptr 1
		.amdhsa_user_sgpr_dispatch_id 0
		.amdhsa_user_sgpr_kernarg_preload_length 0
		.amdhsa_user_sgpr_kernarg_preload_offset 0
		.amdhsa_user_sgpr_private_segment_size 0
		.amdhsa_uses_dynamic_stack 0
		.amdhsa_enable_private_segment 0
		.amdhsa_system_sgpr_workgroup_id_x 1
		.amdhsa_system_sgpr_workgroup_id_y 0
		.amdhsa_system_sgpr_workgroup_id_z 0
		.amdhsa_system_sgpr_workgroup_info 0
		.amdhsa_system_vgpr_workitem_id 2
		.amdhsa_next_free_vgpr 256
		.amdhsa_next_free_sgpr 100
		.amdhsa_accum_offset 256
		.amdhsa_reserve_vcc 1
		.amdhsa_float_round_mode_32 0
		.amdhsa_float_round_mode_16_64 0
		.amdhsa_float_denorm_mode_32 3
		.amdhsa_float_denorm_mode_16_64 3
		.amdhsa_dx10_clamp 1
		.amdhsa_ieee_mode 1
		.amdhsa_fp16_overflow 0
		.amdhsa_tg_split 0
		.amdhsa_exception_fp_ieee_invalid_op 0
		.amdhsa_exception_fp_denorm_src 0
		.amdhsa_exception_fp_ieee_div_zero 0
		.amdhsa_exception_fp_ieee_overflow 0
		.amdhsa_exception_fp_ieee_underflow 0
		.amdhsa_exception_fp_ieee_inexact 0
		.amdhsa_exception_int_div_zero 0
	.end_amdhsa_kernel

amdhsa.kernels:
  - .agpr_count:     0
    .args:
      - .offset:         0
        .size:           3424
        .value_kind:     by_value
      - .offset:         3424
        .size:           4
        .value_kind:     by_value
      - .offset:         3428
        .size:           4
        .value_kind:     by_value
      - .offset:         3432
        .size:           4
        .value_kind:     hidden_block_count_x
      - .offset:         3436
        .size:           4
        .value_kind:     hidden_block_count_y
      - .offset:         3440
        .size:           4
        .value_kind:     hidden_block_count_z
      - .offset:         3444
        .size:           2
        .value_kind:     hidden_group_size_x
      - .offset:         3446
        .size:           2
        .value_kind:     hidden_group_size_y
      - .offset:         3448
        .size:           2
        .value_kind:     hidden_group_size_z
      - .offset:         3450
        .size:           2
        .value_kind:     hidden_remainder_x
      - .offset:         3452
        .size:           2
        .value_kind:     hidden_remainder_y
      - .offset:         3454
        .size:           2
        .value_kind:     hidden_remainder_z
      - .offset:         3472
        .size:           8
        .value_kind:     hidden_global_offset_x
      - .offset:         3480
        .size:           8
        .value_kind:     hidden_global_offset_y
      - .offset:         3488
        .size:           8
        .value_kind:     hidden_global_offset_z
      - .offset:         3496
        .size:           2
        .value_kind:     hidden_grid_dims
      - .offset:         3520
        .size:           8
        .value_kind:     hidden_multigrid_sync_arg
      - .offset:         3552
        .size:           4
        .value_kind:     hidden_dynamic_lds_size
    .group_segment_fixed_size: 16
    .kernarg_segment_align: 8
    .kernarg_segment_size: 3688
    .language:       OpenCL C
    .language_version:
      - 2
      - 0
    .max_flat_workgroup_size: 256
    .name:           _Z4mega6Paramsii
    .private_segment_fixed_size: 0
    .sgpr_count:     106
    .sgpr_spill_count: 174
    .symbol:         _Z4mega6Paramsii.kd
    .uniform_work_group_size: 1
    .uses_dynamic_stack: false
    .vgpr_count:     256
    .vgpr_spill_count: 0
    .wavefront_size: 64
